# BM selected-attention fast path: transcendental and regular VALU alternated one-for-one (exps of tile t between the scale/bias, lane-sum and fp8-convert ops of neighbouring tiles)
# speedup vs baseline: 1.0047x; 1.0047x over previous
.Lbm2_nostag:
.Lbm2_blkA:
	s_lshl_b32 s12, s15, 12
	s_add_u32 s30, s62, s12
	s_addc_u32 s31, s63, 0
	global_load_dwordx4 v[52:55], v79, s[30:31]
	global_load_dwordx4 v[56:59], v79, s[30:31] offset:1024
	global_load_dwordx4 v[60:63], v79, s[30:31] offset:2048
	global_load_dwordx4 v[64:67], v79, s[30:31] offset:3072
	s_add_i32 s14, s35, 3
	s_add_i32 s13, s25, -1
	s_min_i32 s14, s14, s13
	s_lshl_b32 s13, s14, 2
	s_add_i32 s13, s13, s96
	v_mov_b32_e32 v76, s13
	ds_read_b32 v76, v76 offset:16384
	s_cmp_ge_i32 s54, s21
	s_cselect_b32 s14, 1, 0
	s_bfe_u32 s29, s48, 0x40000
	s_cmp_eq_u32 s29, 0
	s_cbranch_scc1 .Lbm2_Ag0_skip
	s_waitcnt vmcnt(12)
	v_mfma_f32_16x16x32_fp8_fp8 v[84:87], v[2:3], v[164:165], 0
	v_mfma_f32_16x16x32_fp8_fp8 v[84:87], v[4:5], v[166:167], v[84:87]
	v_mfma_f32_16x16x32_fp8_fp8 v[88:91], v[6:7], v[164:165], 0
	v_mfma_f32_16x16x32_fp8_fp8 v[88:91], v[8:9], v[166:167], v[88:91]
	v_and_b32_e32 v199, s29, v244
	s_cmp_eq_u32 s14, 1
	v_cmp_ne_u32_e32 vcc, 0, v199
	s_cbranch_scc1 .Lbm2_Ag0_near0
	v_add_f32_e32 v200, v81, v190
	v_cndmask_b32_e32 v200, v77, v200, vcc
	s_cmp_eq_u32 s35, 0
	s_cbranch_scc1 .Lbm2_Ag0_first0
	v_mfma_f32_16x16x32_fp8_fp8 v[92:95], v[12:13], v[164:165], 0
	v_mfma_f32_16x16x32_fp8_fp8 v[92:95], v[14:15], v[166:167], v[92:95]
	v_pk_fma_f32 v[84:85], v[84:85], s[16:17], v[200:201] op_sel_hi:[1,1,0]
	v_pk_fma_f32 v[86:87], v[86:87], s[16:17], v[200:201] op_sel_hi:[1,1,0]
	v_mfma_f32_16x16x32_fp8_fp8 v[96:99], v[16:17], v[164:165], 0
	v_mfma_f32_16x16x32_fp8_fp8 v[96:99], v[18:19], v[166:167], v[96:99]
	v_exp_f32_e32 v84, v84
	v_pk_fma_f32 v[88:89], v[88:89], s[16:17], v[200:201] op_sel_hi:[1,1,0]
	v_exp_f32_e32 v85, v85
	v_pk_fma_f32 v[90:91], v[90:91], s[16:17], v[200:201] op_sel_hi:[1,1,0]
	v_exp_f32_e32 v86, v86
	v_pk_fma_f32 v[92:93], v[92:93], s[16:17], v[200:201] op_sel_hi:[1,1,0]
	v_exp_f32_e32 v87, v87
	v_pk_fma_f32 v[94:95], v[94:95], s[16:17], v[200:201] op_sel_hi:[1,1,0]
	v_exp_f32_e32 v88, v88
	v_pk_fma_f32 v[96:97], v[96:97], s[16:17], v[200:201] op_sel_hi:[1,1,0]
	v_exp_f32_e32 v89, v89
	v_pk_fma_f32 v[98:99], v[98:99], s[16:17], v[200:201] op_sel_hi:[1,1,0]
	v_exp_f32_e32 v90, v90
	v_pk_add_f32 v[248:249], v[84:85], v[86:87]
	v_exp_f32_e32 v91, v91
	v_cvt_pk_fp8_f32 v84, v84, v85
	v_exp_f32_e32 v92, v92
	v_pk_add_f32 v[82:83], v[88:89], v[90:91]
	v_exp_f32_e32 v93, v93
	v_cvt_pk_fp8_f32 v84, v86, v87 op_sel:[0,0,1]
	v_exp_f32_e32 v94, v94
	v_cvt_pk_fp8_f32 v85, v88, v89
	v_exp_f32_e32 v95, v95
	v_cvt_pk_fp8_f32 v85, v90, v91 op_sel:[0,0,1]
	v_exp_f32_e32 v96, v96
	v_pk_add_f32 v[172:173], v[92:93], v[94:95]
	v_exp_f32_e32 v97, v97
	v_pk_add_f32 v[248:249], v[248:249], v[82:83]
	v_exp_f32_e32 v98, v98
	v_cvt_pk_fp8_f32 v86, v92, v93
	v_exp_f32_e32 v99, v99
	v_cvt_pk_fp8_f32 v86, v94, v95 op_sel:[0,0,1]
	v_pk_add_f32 v[202:203], v[96:97], v[98:99]
	v_cvt_pk_fp8_f32 v87, v96, v97
	v_pk_add_f32 v[172:173], v[172:173], v[202:203]
	v_cvt_pk_fp8_f32 v87, v98, v99 op_sel:[0,0,1]
	v_pk_add_f32 v[248:249], v[248:249], v[172:173]
	s_nop 0
	v_add_f32_e32 v248, v248, v249
	v_cmp_lt_f32_e32 vcc, 0x43800000, v248
	s_cbranch_vccnz .Lbm2_Ag0_redo
	s_lshr_b32 s83, s48, 4
	s_cmp_lg_u32 s83, 0
	s_cbranch_scc1 .Lbm2_Ag0_ks0
	s_lshl_b32 s83, s32, 12
	s_add_u32 s30, s46, s83
	s_addc_u32 s31, s47, 0
	global_load_dwordx4 v[2:5], v79, s[30:31]
	global_load_dwordx4 v[6:9], v79, s[30:31] offset:1024
	global_load_dwordx4 v[12:15], v79, s[30:31] offset:2048
	global_load_dwordx4 v[16:19], v79, s[30:31] offset:3072

.Lbm2_Ag0_skip:
	s_bfe_u32 s29, s48, 0x40004
	s_cmp_eq_u32 s29, 0
	s_cbranch_scc1 .Lbm2_Ag1_skip
	s_waitcnt vmcnt(12)
	v_mfma_f32_16x16x32_fp8_fp8 v[84:87], v[2:3], v[168:169], 0
	v_mfma_f32_16x16x32_fp8_fp8 v[84:87], v[4:5], v[170:171], v[84:87]
	v_mfma_f32_16x16x32_fp8_fp8 v[88:91], v[6:7], v[168:169], 0
	v_mfma_f32_16x16x32_fp8_fp8 v[88:91], v[8:9], v[170:171], v[88:91]
	v_and_b32_e32 v199, s29, v244
	s_cmp_eq_u32 s14, 1
	v_cmp_ne_u32_e32 vcc, 0, v199
	s_cbranch_scc1 .Lbm2_Ag1_near0
	v_add_f32_e32 v200, v81, v191
	v_cndmask_b32_e32 v200, v77, v200, vcc
	s_cmp_eq_u32 s35, 0
	s_cbranch_scc1 .Lbm2_Ag1_first0
	v_mfma_f32_16x16x32_fp8_fp8 v[92:95], v[12:13], v[168:169], 0
	v_mfma_f32_16x16x32_fp8_fp8 v[92:95], v[14:15], v[170:171], v[92:95]
	v_pk_fma_f32 v[84:85], v[84:85], s[16:17], v[200:201] op_sel_hi:[1,1,0]
	v_pk_fma_f32 v[86:87], v[86:87], s[16:17], v[200:201] op_sel_hi:[1,1,0]
	v_mfma_f32_16x16x32_fp8_fp8 v[96:99], v[16:17], v[168:169], 0
	v_mfma_f32_16x16x32_fp8_fp8 v[96:99], v[18:19], v[170:171], v[96:99]
	v_exp_f32_e32 v84, v84
	v_pk_fma_f32 v[88:89], v[88:89], s[16:17], v[200:201] op_sel_hi:[1,1,0]
	v_exp_f32_e32 v85, v85
	v_pk_fma_f32 v[90:91], v[90:91], s[16:17], v[200:201] op_sel_hi:[1,1,0]
	v_exp_f32_e32 v86, v86
	v_pk_fma_f32 v[92:93], v[92:93], s[16:17], v[200:201] op_sel_hi:[1,1,0]
	v_exp_f32_e32 v87, v87
	v_pk_fma_f32 v[94:95], v[94:95], s[16:17], v[200:201] op_sel_hi:[1,1,0]
	v_exp_f32_e32 v88, v88
	v_pk_fma_f32 v[96:97], v[96:97], s[16:17], v[200:201] op_sel_hi:[1,1,0]
	v_exp_f32_e32 v89, v89
	v_pk_fma_f32 v[98:99], v[98:99], s[16:17], v[200:201] op_sel_hi:[1,1,0]
	v_exp_f32_e32 v90, v90
	v_pk_add_f32 v[248:249], v[84:85], v[86:87]
	v_exp_f32_e32 v91, v91
	v_cvt_pk_fp8_f32 v84, v84, v85
	v_exp_f32_e32 v92, v92
	v_pk_add_f32 v[82:83], v[88:89], v[90:91]
	v_exp_f32_e32 v93, v93
	v_cvt_pk_fp8_f32 v84, v86, v87 op_sel:[0,0,1]
	v_exp_f32_e32 v94, v94
	v_cvt_pk_fp8_f32 v85, v88, v89
	v_exp_f32_e32 v95, v95
	v_cvt_pk_fp8_f32 v85, v90, v91 op_sel:[0,0,1]
	v_exp_f32_e32 v96, v96
	v_pk_add_f32 v[172:173], v[92:93], v[94:95]
	v_exp_f32_e32 v97, v97
	v_pk_add_f32 v[248:249], v[248:249], v[82:83]
	v_exp_f32_e32 v98, v98
	v_cvt_pk_fp8_f32 v86, v92, v93
	v_exp_f32_e32 v99, v99
	v_cvt_pk_fp8_f32 v86, v94, v95 op_sel:[0,0,1]
	v_pk_add_f32 v[202:203], v[96:97], v[98:99]
	v_cvt_pk_fp8_f32 v87, v96, v97
	v_pk_add_f32 v[172:173], v[172:173], v[202:203]
	v_cvt_pk_fp8_f32 v87, v98, v99 op_sel:[0,0,1]
	v_pk_add_f32 v[248:249], v[248:249], v[172:173]
	s_nop 0
	v_add_f32_e32 v248, v248, v249
	v_cmp_lt_f32_e32 vcc, 0x43800000, v248
	s_cbranch_vccnz .Lbm2_Ag1_redo
	s_lshr_b32 s83, s48, 8
	s_cmp_lg_u32 s83, 0
	s_cbranch_scc1 .Lbm2_Ag1_ks0
	s_lshl_b32 s83, s32, 12
	s_add_u32 s30, s46, s83
	s_addc_u32 s31, s47, 0
	global_load_dwordx4 v[2:5], v79, s[30:31]
	global_load_dwordx4 v[6:9], v79, s[30:31] offset:1024
	global_load_dwordx4 v[12:15], v79, s[30:31] offset:2048
	global_load_dwordx4 v[16:19], v79, s[30:31] offset:3072

.Lbm2_Ag1_skip:
	s_bfe_u32 s29, s48, 0x40008
	s_cmp_eq_u32 s29, 0
	s_cbranch_scc1 .Lbm2_Ag2_skip
	s_waitcnt vmcnt(12)
	v_mfma_f32_16x16x32_fp8_fp8 v[84:87], v[2:3], v[182:183], 0
	v_mfma_f32_16x16x32_fp8_fp8 v[84:87], v[4:5], v[184:185], v[84:87]
	v_mfma_f32_16x16x32_fp8_fp8 v[88:91], v[6:7], v[182:183], 0
	v_mfma_f32_16x16x32_fp8_fp8 v[88:91], v[8:9], v[184:185], v[88:91]
	v_and_b32_e32 v199, s29, v244
	s_cmp_eq_u32 s14, 1
	v_cmp_ne_u32_e32 vcc, 0, v199
	s_cbranch_scc1 .Lbm2_Ag2_near0
	v_add_f32_e32 v200, v81, v192
	v_cndmask_b32_e32 v200, v77, v200, vcc
	s_cmp_eq_u32 s35, 0
	s_cbranch_scc1 .Lbm2_Ag2_first0
	v_mfma_f32_16x16x32_fp8_fp8 v[92:95], v[12:13], v[182:183], 0
	v_mfma_f32_16x16x32_fp8_fp8 v[92:95], v[14:15], v[184:185], v[92:95]
	v_pk_fma_f32 v[84:85], v[84:85], s[16:17], v[200:201] op_sel_hi:[1,1,0]
	v_pk_fma_f32 v[86:87], v[86:87], s[16:17], v[200:201] op_sel_hi:[1,1,0]
	v_mfma_f32_16x16x32_fp8_fp8 v[96:99], v[16:17], v[182:183], 0
	v_mfma_f32_16x16x32_fp8_fp8 v[96:99], v[18:19], v[184:185], v[96:99]
	v_exp_f32_e32 v84, v84
	v_pk_fma_f32 v[88:89], v[88:89], s[16:17], v[200:201] op_sel_hi:[1,1,0]
	v_exp_f32_e32 v85, v85
	v_pk_fma_f32 v[90:91], v[90:91], s[16:17], v[200:201] op_sel_hi:[1,1,0]
	v_exp_f32_e32 v86, v86
	v_pk_fma_f32 v[92:93], v[92:93], s[16:17], v[200:201] op_sel_hi:[1,1,0]
	v_exp_f32_e32 v87, v87
	v_pk_fma_f32 v[94:95], v[94:95], s[16:17], v[200:201] op_sel_hi:[1,1,0]
	v_exp_f32_e32 v88, v88
	v_pk_fma_f32 v[96:97], v[96:97], s[16:17], v[200:201] op_sel_hi:[1,1,0]
	v_exp_f32_e32 v89, v89
	v_pk_fma_f32 v[98:99], v[98:99], s[16:17], v[200:201] op_sel_hi:[1,1,0]
	v_exp_f32_e32 v90, v90
	v_pk_add_f32 v[248:249], v[84:85], v[86:87]
	v_exp_f32_e32 v91, v91
	v_cvt_pk_fp8_f32 v84, v84, v85
	v_exp_f32_e32 v92, v92
	v_pk_add_f32 v[82:83], v[88:89], v[90:91]
	v_exp_f32_e32 v93, v93
	v_cvt_pk_fp8_f32 v84, v86, v87 op_sel:[0,0,1]
	v_exp_f32_e32 v94, v94
	v_cvt_pk_fp8_f32 v85, v88, v89
	v_exp_f32_e32 v95, v95
	v_cvt_pk_fp8_f32 v85, v90, v91 op_sel:[0,0,1]
	v_exp_f32_e32 v96, v96
	v_pk_add_f32 v[172:173], v[92:93], v[94:95]
	v_exp_f32_e32 v97, v97
	v_pk_add_f32 v[248:249], v[248:249], v[82:83]
	v_exp_f32_e32 v98, v98
	v_cvt_pk_fp8_f32 v86, v92, v93
	v_exp_f32_e32 v99, v99
	v_cvt_pk_fp8_f32 v86, v94, v95 op_sel:[0,0,1]
	v_pk_add_f32 v[202:203], v[96:97], v[98:99]
	v_cvt_pk_fp8_f32 v87, v96, v97
	v_pk_add_f32 v[172:173], v[172:173], v[202:203]
	v_cvt_pk_fp8_f32 v87, v98, v99 op_sel:[0,0,1]
	v_pk_add_f32 v[248:249], v[248:249], v[172:173]
	s_nop 0
	v_add_f32_e32 v248, v248, v249
	v_cmp_lt_f32_e32 vcc, 0x43800000, v248
	s_cbranch_vccnz .Lbm2_Ag2_redo
	s_lshr_b32 s83, s48, 12
	s_cmp_lg_u32 s83, 0
	s_cbranch_scc1 .Lbm2_Ag2_ks0
	s_lshl_b32 s83, s32, 12
	s_add_u32 s30, s46, s83
	s_addc_u32 s31, s47, 0
	global_load_dwordx4 v[2:5], v79, s[30:31]
	global_load_dwordx4 v[6:9], v79, s[30:31] offset:1024
	global_load_dwordx4 v[12:15], v79, s[30:31] offset:2048
	global_load_dwordx4 v[16:19], v79, s[30:31] offset:3072

.Lbm2_Ag2_skip:
	s_bfe_u32 s29, s48, 0x4000c
	s_cmp_eq_u32 s29, 0
	s_cbranch_scc1 .Lbm2_Ag3_skip
	s_waitcnt vmcnt(12)
	v_mfma_f32_16x16x32_fp8_fp8 v[84:87], v[2:3], v[186:187], 0
	v_mfma_f32_16x16x32_fp8_fp8 v[84:87], v[4:5], v[188:189], v[84:87]
	v_mfma_f32_16x16x32_fp8_fp8 v[88:91], v[6:7], v[186:187], 0
	v_mfma_f32_16x16x32_fp8_fp8 v[88:91], v[8:9], v[188:189], v[88:91]
	v_and_b32_e32 v199, s29, v244
	s_cmp_eq_u32 s14, 1
	v_cmp_ne_u32_e32 vcc, 0, v199
	s_cbranch_scc1 .Lbm2_Ag3_near0
	v_add_f32_e32 v200, v81, v193
	v_cndmask_b32_e32 v200, v77, v200, vcc
	s_cmp_eq_u32 s35, 0
	s_cbranch_scc1 .Lbm2_Ag3_first0
	v_mfma_f32_16x16x32_fp8_fp8 v[92:95], v[12:13], v[186:187], 0
	v_mfma_f32_16x16x32_fp8_fp8 v[92:95], v[14:15], v[188:189], v[92:95]
	v_pk_fma_f32 v[84:85], v[84:85], s[16:17], v[200:201] op_sel_hi:[1,1,0]
	v_pk_fma_f32 v[86:87], v[86:87], s[16:17], v[200:201] op_sel_hi:[1,1,0]
	v_mfma_f32_16x16x32_fp8_fp8 v[96:99], v[16:17], v[186:187], 0
	v_mfma_f32_16x16x32_fp8_fp8 v[96:99], v[18:19], v[188:189], v[96:99]
	v_exp_f32_e32 v84, v84
	v_pk_fma_f32 v[88:89], v[88:89], s[16:17], v[200:201] op_sel_hi:[1,1,0]
	v_exp_f32_e32 v85, v85
	v_pk_fma_f32 v[90:91], v[90:91], s[16:17], v[200:201] op_sel_hi:[1,1,0]
	v_exp_f32_e32 v86, v86
	v_pk_fma_f32 v[92:93], v[92:93], s[16:17], v[200:201] op_sel_hi:[1,1,0]
	v_exp_f32_e32 v87, v87
	v_pk_fma_f32 v[94:95], v[94:95], s[16:17], v[200:201] op_sel_hi:[1,1,0]
	v_exp_f32_e32 v88, v88
	v_pk_fma_f32 v[96:97], v[96:97], s[16:17], v[200:201] op_sel_hi:[1,1,0]
	v_exp_f32_e32 v89, v89
	v_pk_fma_f32 v[98:99], v[98:99], s[16:17], v[200:201] op_sel_hi:[1,1,0]
	v_exp_f32_e32 v90, v90
	v_pk_add_f32 v[248:249], v[84:85], v[86:87]
	v_exp_f32_e32 v91, v91
	v_cvt_pk_fp8_f32 v84, v84, v85
	v_exp_f32_e32 v92, v92
	v_pk_add_f32 v[82:83], v[88:89], v[90:91]
	v_exp_f32_e32 v93, v93
	v_cvt_pk_fp8_f32 v84, v86, v87 op_sel:[0,0,1]
	v_exp_f32_e32 v94, v94
	v_cvt_pk_fp8_f32 v85, v88, v89
	v_exp_f32_e32 v95, v95
	v_cvt_pk_fp8_f32 v85, v90, v91 op_sel:[0,0,1]
	v_exp_f32_e32 v96, v96
	v_pk_add_f32 v[172:173], v[92:93], v[94:95]
	v_exp_f32_e32 v97, v97
	v_pk_add_f32 v[248:249], v[248:249], v[82:83]
	v_exp_f32_e32 v98, v98
	v_cvt_pk_fp8_f32 v86, v92, v93
	v_exp_f32_e32 v99, v99
	v_cvt_pk_fp8_f32 v86, v94, v95 op_sel:[0,0,1]
	v_pk_add_f32 v[202:203], v[96:97], v[98:99]
	v_cvt_pk_fp8_f32 v87, v96, v97
	v_pk_add_f32 v[172:173], v[172:173], v[202:203]
	v_cvt_pk_fp8_f32 v87, v98, v99 op_sel:[0,0,1]
	v_pk_add_f32 v[248:249], v[248:249], v[172:173]
	s_nop 0
	v_add_f32_e32 v248, v248, v249
	v_cmp_lt_f32_e32 vcc, 0x43800000, v248
	s_cbranch_vccnz .Lbm2_Ag3_redo
	s_lshl_b32 s83, s32, 12
	s_add_u32 s30, s46, s83
	s_addc_u32 s31, s47, 0
	global_load_dwordx4 v[2:5], v79, s[30:31]
	global_load_dwordx4 v[6:9], v79, s[30:31] offset:1024
	global_load_dwordx4 v[12:15], v79, s[30:31] offset:2048
	global_load_dwordx4 v[16:19], v79, s[30:31] offset:3072
	v_add_f32_e32 v197, v197, v248
	s_waitcnt vmcnt(8)
	v_mfma_f32_16x16x32_fp8_fp8 v[148:151], v[36:37], v[84:85], v[148:151]
	v_mfma_f32_16x16x32_fp8_fp8 v[152:155], v[38:39], v[84:85], v[152:155]
	v_mfma_f32_16x16x32_fp8_fp8 v[156:159], v[40:41], v[84:85], v[156:159]
	v_mfma_f32_16x16x32_fp8_fp8 v[160:163], v[42:43], v[84:85], v[160:163]
	v_mfma_f32_16x16x32_fp8_fp8 v[148:151], v[44:45], v[86:87], v[148:151]
	v_mfma_f32_16x16x32_fp8_fp8 v[152:155], v[46:47], v[86:87], v[152:155]
	v_mfma_f32_16x16x32_fp8_fp8 v[156:159], v[48:49], v[86:87], v[156:159]
	v_mfma_f32_16x16x32_fp8_fp8 v[160:163], v[50:51], v[86:87], v[160:163]
	s_branch .Lbm2_Ag3_skip

.Lbm2_blkB:
	s_lshl_b32 s12, s15, 12
	s_add_u32 s30, s62, s12
	s_addc_u32 s31, s63, 0
	global_load_dwordx4 v[36:39], v79, s[30:31]
	global_load_dwordx4 v[40:43], v79, s[30:31] offset:1024
	global_load_dwordx4 v[44:47], v79, s[30:31] offset:2048
	global_load_dwordx4 v[48:51], v79, s[30:31] offset:3072
	s_add_i32 s14, s35, 3
	s_add_i32 s13, s25, -1
	s_min_i32 s14, s14, s13
	s_lshl_b32 s13, s14, 2
	s_add_i32 s13, s13, s96
	v_mov_b32_e32 v76, s13
	ds_read_b32 v76, v76 offset:16384
	s_cmp_ge_i32 s54, s21
	s_cselect_b32 s14, 1, 0
	s_bfe_u32 s29, s48, 0x40000
	s_cmp_eq_u32 s29, 0
	s_cbranch_scc1 .Lbm2_Bg0_skip
	s_waitcnt vmcnt(12)
	v_mfma_f32_16x16x32_fp8_fp8 v[84:87], v[20:21], v[164:165], 0
	v_mfma_f32_16x16x32_fp8_fp8 v[84:87], v[22:23], v[166:167], v[84:87]
	v_mfma_f32_16x16x32_fp8_fp8 v[88:91], v[24:25], v[164:165], 0
	v_mfma_f32_16x16x32_fp8_fp8 v[88:91], v[26:27], v[166:167], v[88:91]
	v_and_b32_e32 v199, s29, v244
	s_cmp_eq_u32 s14, 1
	v_cmp_ne_u32_e32 vcc, 0, v199
	s_cbranch_scc1 .Lbm2_Bg0_near0
	v_add_f32_e32 v200, v81, v190
	v_cndmask_b32_e32 v200, v77, v200, vcc
	s_cmp_eq_u32 s35, 0
	s_cbranch_scc1 .Lbm2_Bg0_first0
	v_mfma_f32_16x16x32_fp8_fp8 v[92:95], v[28:29], v[164:165], 0
	v_mfma_f32_16x16x32_fp8_fp8 v[92:95], v[30:31], v[166:167], v[92:95]
	v_pk_fma_f32 v[84:85], v[84:85], s[16:17], v[200:201] op_sel_hi:[1,1,0]
	v_pk_fma_f32 v[86:87], v[86:87], s[16:17], v[200:201] op_sel_hi:[1,1,0]
	v_mfma_f32_16x16x32_fp8_fp8 v[96:99], v[32:33], v[164:165], 0
	v_mfma_f32_16x16x32_fp8_fp8 v[96:99], v[34:35], v[166:167], v[96:99]
	v_exp_f32_e32 v84, v84
	v_pk_fma_f32 v[88:89], v[88:89], s[16:17], v[200:201] op_sel_hi:[1,1,0]
	v_exp_f32_e32 v85, v85
	v_pk_fma_f32 v[90:91], v[90:91], s[16:17], v[200:201] op_sel_hi:[1,1,0]
	v_exp_f32_e32 v86, v86
	v_pk_fma_f32 v[92:93], v[92:93], s[16:17], v[200:201] op_sel_hi:[1,1,0]
	v_exp_f32_e32 v87, v87
	v_pk_fma_f32 v[94:95], v[94:95], s[16:17], v[200:201] op_sel_hi:[1,1,0]
	v_exp_f32_e32 v88, v88
	v_pk_fma_f32 v[96:97], v[96:97], s[16:17], v[200:201] op_sel_hi:[1,1,0]
	v_exp_f32_e32 v89, v89
	v_pk_fma_f32 v[98:99], v[98:99], s[16:17], v[200:201] op_sel_hi:[1,1,0]
	v_exp_f32_e32 v90, v90
	v_pk_add_f32 v[248:249], v[84:85], v[86:87]
	v_exp_f32_e32 v91, v91
	v_cvt_pk_fp8_f32 v84, v84, v85
	v_exp_f32_e32 v92, v92
	v_pk_add_f32 v[82:83], v[88:89], v[90:91]
	v_exp_f32_e32 v93, v93
	v_cvt_pk_fp8_f32 v84, v86, v87 op_sel:[0,0,1]
	v_exp_f32_e32 v94, v94
	v_cvt_pk_fp8_f32 v85, v88, v89
	v_exp_f32_e32 v95, v95
	v_cvt_pk_fp8_f32 v85, v90, v91 op_sel:[0,0,1]
	v_exp_f32_e32 v96, v96
	v_pk_add_f32 v[172:173], v[92:93], v[94:95]
	v_exp_f32_e32 v97, v97
	v_pk_add_f32 v[248:249], v[248:249], v[82:83]
	v_exp_f32_e32 v98, v98
	v_cvt_pk_fp8_f32 v86, v92, v93
	v_exp_f32_e32 v99, v99
	v_cvt_pk_fp8_f32 v86, v94, v95 op_sel:[0,0,1]
	v_pk_add_f32 v[202:203], v[96:97], v[98:99]
	v_cvt_pk_fp8_f32 v87, v96, v97
	v_pk_add_f32 v[172:173], v[172:173], v[202:203]
	v_cvt_pk_fp8_f32 v87, v98, v99 op_sel:[0,0,1]
	v_pk_add_f32 v[248:249], v[248:249], v[172:173]
	s_nop 0
	v_add_f32_e32 v248, v248, v249
	v_cmp_lt_f32_e32 vcc, 0x43800000, v248
	s_cbranch_vccnz .Lbm2_Bg0_redo
	s_lshr_b32 s83, s48, 4
	s_cmp_lg_u32 s83, 0
	s_cbranch_scc1 .Lbm2_Bg0_ks0
	s_lshl_b32 s83, s32, 12
	s_add_u32 s30, s46, s83
	s_addc_u32 s31, s47, 0
	global_load_dwordx4 v[20:23], v79, s[30:31]
	global_load_dwordx4 v[24:27], v79, s[30:31] offset:1024
	global_load_dwordx4 v[28:31], v79, s[30:31] offset:2048
	global_load_dwordx4 v[32:35], v79, s[30:31] offset:3072

.Lbm2_Bg0_skip:
	s_bfe_u32 s29, s48, 0x40004
	s_cmp_eq_u32 s29, 0
	s_cbranch_scc1 .Lbm2_Bg1_skip
	s_waitcnt vmcnt(12)
	v_mfma_f32_16x16x32_fp8_fp8 v[84:87], v[20:21], v[168:169], 0
	v_mfma_f32_16x16x32_fp8_fp8 v[84:87], v[22:23], v[170:171], v[84:87]
	v_mfma_f32_16x16x32_fp8_fp8 v[88:91], v[24:25], v[168:169], 0
	v_mfma_f32_16x16x32_fp8_fp8 v[88:91], v[26:27], v[170:171], v[88:91]
	v_and_b32_e32 v199, s29, v244
	s_cmp_eq_u32 s14, 1
	v_cmp_ne_u32_e32 vcc, 0, v199
	s_cbranch_scc1 .Lbm2_Bg1_near0
	v_add_f32_e32 v200, v81, v191
	v_cndmask_b32_e32 v200, v77, v200, vcc
	s_cmp_eq_u32 s35, 0
	s_cbranch_scc1 .Lbm2_Bg1_first0
	v_mfma_f32_16x16x32_fp8_fp8 v[92:95], v[28:29], v[168:169], 0
	v_mfma_f32_16x16x32_fp8_fp8 v[92:95], v[30:31], v[170:171], v[92:95]
	v_pk_fma_f32 v[84:85], v[84:85], s[16:17], v[200:201] op_sel_hi:[1,1,0]
	v_pk_fma_f32 v[86:87], v[86:87], s[16:17], v[200:201] op_sel_hi:[1,1,0]
	v_mfma_f32_16x16x32_fp8_fp8 v[96:99], v[32:33], v[168:169], 0
	v_mfma_f32_16x16x32_fp8_fp8 v[96:99], v[34:35], v[170:171], v[96:99]
	v_exp_f32_e32 v84, v84
	v_pk_fma_f32 v[88:89], v[88:89], s[16:17], v[200:201] op_sel_hi:[1,1,0]
	v_exp_f32_e32 v85, v85
	v_pk_fma_f32 v[90:91], v[90:91], s[16:17], v[200:201] op_sel_hi:[1,1,0]
	v_exp_f32_e32 v86, v86
	v_pk_fma_f32 v[92:93], v[92:93], s[16:17], v[200:201] op_sel_hi:[1,1,0]
	v_exp_f32_e32 v87, v87
	v_pk_fma_f32 v[94:95], v[94:95], s[16:17], v[200:201] op_sel_hi:[1,1,0]
	v_exp_f32_e32 v88, v88
	v_pk_fma_f32 v[96:97], v[96:97], s[16:17], v[200:201] op_sel_hi:[1,1,0]
	v_exp_f32_e32 v89, v89
	v_pk_fma_f32 v[98:99], v[98:99], s[16:17], v[200:201] op_sel_hi:[1,1,0]
	v_exp_f32_e32 v90, v90
	v_pk_add_f32 v[248:249], v[84:85], v[86:87]
	v_exp_f32_e32 v91, v91
	v_cvt_pk_fp8_f32 v84, v84, v85
	v_exp_f32_e32 v92, v92
	v_pk_add_f32 v[82:83], v[88:89], v[90:91]
	v_exp_f32_e32 v93, v93
	v_cvt_pk_fp8_f32 v84, v86, v87 op_sel:[0,0,1]
	v_exp_f32_e32 v94, v94
	v_cvt_pk_fp8_f32 v85, v88, v89
	v_exp_f32_e32 v95, v95
	v_cvt_pk_fp8_f32 v85, v90, v91 op_sel:[0,0,1]
	v_exp_f32_e32 v96, v96
	v_pk_add_f32 v[172:173], v[92:93], v[94:95]
	v_exp_f32_e32 v97, v97
	v_pk_add_f32 v[248:249], v[248:249], v[82:83]
	v_exp_f32_e32 v98, v98
	v_cvt_pk_fp8_f32 v86, v92, v93
	v_exp_f32_e32 v99, v99
	v_cvt_pk_fp8_f32 v86, v94, v95 op_sel:[0,0,1]
	v_pk_add_f32 v[202:203], v[96:97], v[98:99]
	v_cvt_pk_fp8_f32 v87, v96, v97
	v_pk_add_f32 v[172:173], v[172:173], v[202:203]
	v_cvt_pk_fp8_f32 v87, v98, v99 op_sel:[0,0,1]
	v_pk_add_f32 v[248:249], v[248:249], v[172:173]
	s_nop 0
	v_add_f32_e32 v248, v248, v249
	v_cmp_lt_f32_e32 vcc, 0x43800000, v248
	s_cbranch_vccnz .Lbm2_Bg1_redo
	s_lshr_b32 s83, s48, 8
	s_cmp_lg_u32 s83, 0
	s_cbranch_scc1 .Lbm2_Bg1_ks0
	s_lshl_b32 s83, s32, 12
	s_add_u32 s30, s46, s83
	s_addc_u32 s31, s47, 0
	global_load_dwordx4 v[20:23], v79, s[30:31]
	global_load_dwordx4 v[24:27], v79, s[30:31] offset:1024
	global_load_dwordx4 v[28:31], v79, s[30:31] offset:2048
	global_load_dwordx4 v[32:35], v79, s[30:31] offset:3072

.Lbm2_Bg1_skip:
	s_bfe_u32 s29, s48, 0x40008
	s_cmp_eq_u32 s29, 0
	s_cbranch_scc1 .Lbm2_Bg2_skip
	s_waitcnt vmcnt(12)
	v_mfma_f32_16x16x32_fp8_fp8 v[84:87], v[20:21], v[182:183], 0
	v_mfma_f32_16x16x32_fp8_fp8 v[84:87], v[22:23], v[184:185], v[84:87]
	v_mfma_f32_16x16x32_fp8_fp8 v[88:91], v[24:25], v[182:183], 0
	v_mfma_f32_16x16x32_fp8_fp8 v[88:91], v[26:27], v[184:185], v[88:91]
	v_and_b32_e32 v199, s29, v244
	s_cmp_eq_u32 s14, 1
	v_cmp_ne_u32_e32 vcc, 0, v199
	s_cbranch_scc1 .Lbm2_Bg2_near0
	v_add_f32_e32 v200, v81, v192
	v_cndmask_b32_e32 v200, v77, v200, vcc
	s_cmp_eq_u32 s35, 0
	s_cbranch_scc1 .Lbm2_Bg2_first0
	v_mfma_f32_16x16x32_fp8_fp8 v[92:95], v[28:29], v[182:183], 0
	v_mfma_f32_16x16x32_fp8_fp8 v[92:95], v[30:31], v[184:185], v[92:95]
	v_pk_fma_f32 v[84:85], v[84:85], s[16:17], v[200:201] op_sel_hi:[1,1,0]
	v_pk_fma_f32 v[86:87], v[86:87], s[16:17], v[200:201] op_sel_hi:[1,1,0]
	v_mfma_f32_16x16x32_fp8_fp8 v[96:99], v[32:33], v[182:183], 0
	v_mfma_f32_16x16x32_fp8_fp8 v[96:99], v[34:35], v[184:185], v[96:99]
	v_exp_f32_e32 v84, v84
	v_pk_fma_f32 v[88:89], v[88:89], s[16:17], v[200:201] op_sel_hi:[1,1,0]
	v_exp_f32_e32 v85, v85
	v_pk_fma_f32 v[90:91], v[90:91], s[16:17], v[200:201] op_sel_hi:[1,1,0]
	v_exp_f32_e32 v86, v86
	v_pk_fma_f32 v[92:93], v[92:93], s[16:17], v[200:201] op_sel_hi:[1,1,0]
	v_exp_f32_e32 v87, v87
	v_pk_fma_f32 v[94:95], v[94:95], s[16:17], v[200:201] op_sel_hi:[1,1,0]
	v_exp_f32_e32 v88, v88
	v_pk_fma_f32 v[96:97], v[96:97], s[16:17], v[200:201] op_sel_hi:[1,1,0]
	v_exp_f32_e32 v89, v89
	v_pk_fma_f32 v[98:99], v[98:99], s[16:17], v[200:201] op_sel_hi:[1,1,0]
	v_exp_f32_e32 v90, v90
	v_pk_add_f32 v[248:249], v[84:85], v[86:87]
	v_exp_f32_e32 v91, v91
	v_cvt_pk_fp8_f32 v84, v84, v85
	v_exp_f32_e32 v92, v92
	v_pk_add_f32 v[82:83], v[88:89], v[90:91]
	v_exp_f32_e32 v93, v93
	v_cvt_pk_fp8_f32 v84, v86, v87 op_sel:[0,0,1]
	v_exp_f32_e32 v94, v94
	v_cvt_pk_fp8_f32 v85, v88, v89
	v_exp_f32_e32 v95, v95
	v_cvt_pk_fp8_f32 v85, v90, v91 op_sel:[0,0,1]
	v_exp_f32_e32 v96, v96
	v_pk_add_f32 v[172:173], v[92:93], v[94:95]
	v_exp_f32_e32 v97, v97
	v_pk_add_f32 v[248:249], v[248:249], v[82:83]
	v_exp_f32_e32 v98, v98
	v_cvt_pk_fp8_f32 v86, v92, v93
	v_exp_f32_e32 v99, v99
	v_cvt_pk_fp8_f32 v86, v94, v95 op_sel:[0,0,1]
	v_pk_add_f32 v[202:203], v[96:97], v[98:99]
	v_cvt_pk_fp8_f32 v87, v96, v97
	v_pk_add_f32 v[172:173], v[172:173], v[202:203]
	v_cvt_pk_fp8_f32 v87, v98, v99 op_sel:[0,0,1]
	v_pk_add_f32 v[248:249], v[248:249], v[172:173]
	s_nop 0
	v_add_f32_e32 v248, v248, v249
	v_cmp_lt_f32_e32 vcc, 0x43800000, v248
	s_cbranch_vccnz .Lbm2_Bg2_redo
	s_lshr_b32 s83, s48, 12
	s_cmp_lg_u32 s83, 0
	s_cbranch_scc1 .Lbm2_Bg2_ks0
	s_lshl_b32 s83, s32, 12
	s_add_u32 s30, s46, s83
	s_addc_u32 s31, s47, 0
	global_load_dwordx4 v[20:23], v79, s[30:31]
	global_load_dwordx4 v[24:27], v79, s[30:31] offset:1024
	global_load_dwordx4 v[28:31], v79, s[30:31] offset:2048
	global_load_dwordx4 v[32:35], v79, s[30:31] offset:3072

.Lbm2_Bg2_skip:
	s_bfe_u32 s29, s48, 0x4000c
	s_cmp_eq_u32 s29, 0
	s_cbranch_scc1 .Lbm2_Bg3_skip
	s_waitcnt vmcnt(12)
	v_mfma_f32_16x16x32_fp8_fp8 v[84:87], v[20:21], v[186:187], 0
	v_mfma_f32_16x16x32_fp8_fp8 v[84:87], v[22:23], v[188:189], v[84:87]
	v_mfma_f32_16x16x32_fp8_fp8 v[88:91], v[24:25], v[186:187], 0
	v_mfma_f32_16x16x32_fp8_fp8 v[88:91], v[26:27], v[188:189], v[88:91]
	v_and_b32_e32 v199, s29, v244
	s_cmp_eq_u32 s14, 1
	v_cmp_ne_u32_e32 vcc, 0, v199
	s_cbranch_scc1 .Lbm2_Bg3_near0
	v_add_f32_e32 v200, v81, v193
	v_cndmask_b32_e32 v200, v77, v200, vcc
	s_cmp_eq_u32 s35, 0
	s_cbranch_scc1 .Lbm2_Bg3_first0
	v_mfma_f32_16x16x32_fp8_fp8 v[92:95], v[28:29], v[186:187], 0
	v_mfma_f32_16x16x32_fp8_fp8 v[92:95], v[30:31], v[188:189], v[92:95]
	v_pk_fma_f32 v[84:85], v[84:85], s[16:17], v[200:201] op_sel_hi:[1,1,0]
	v_pk_fma_f32 v[86:87], v[86:87], s[16:17], v[200:201] op_sel_hi:[1,1,0]
	v_mfma_f32_16x16x32_fp8_fp8 v[96:99], v[32:33], v[186:187], 0
	v_mfma_f32_16x16x32_fp8_fp8 v[96:99], v[34:35], v[188:189], v[96:99]
	v_exp_f32_e32 v84, v84
	v_pk_fma_f32 v[88:89], v[88:89], s[16:17], v[200:201] op_sel_hi:[1,1,0]
	v_exp_f32_e32 v85, v85
	v_pk_fma_f32 v[90:91], v[90:91], s[16:17], v[200:201] op_sel_hi:[1,1,0]
	v_exp_f32_e32 v86, v86
	v_pk_fma_f32 v[92:93], v[92:93], s[16:17], v[200:201] op_sel_hi:[1,1,0]
	v_exp_f32_e32 v87, v87
	v_pk_fma_f32 v[94:95], v[94:95], s[16:17], v[200:201] op_sel_hi:[1,1,0]
	v_exp_f32_e32 v88, v88
	v_pk_fma_f32 v[96:97], v[96:97], s[16:17], v[200:201] op_sel_hi:[1,1,0]
	v_exp_f32_e32 v89, v89
	v_pk_fma_f32 v[98:99], v[98:99], s[16:17], v[200:201] op_sel_hi:[1,1,0]
	v_exp_f32_e32 v90, v90
	v_pk_add_f32 v[248:249], v[84:85], v[86:87]
	v_exp_f32_e32 v91, v91
	v_cvt_pk_fp8_f32 v84, v84, v85
	v_exp_f32_e32 v92, v92
	v_pk_add_f32 v[82:83], v[88:89], v[90:91]
	v_exp_f32_e32 v93, v93
	v_cvt_pk_fp8_f32 v84, v86, v87 op_sel:[0,0,1]
	v_exp_f32_e32 v94, v94
	v_cvt_pk_fp8_f32 v85, v88, v89
	v_exp_f32_e32 v95, v95
	v_cvt_pk_fp8_f32 v85, v90, v91 op_sel:[0,0,1]
	v_exp_f32_e32 v96, v96
	v_pk_add_f32 v[172:173], v[92:93], v[94:95]
	v_exp_f32_e32 v97, v97
	v_pk_add_f32 v[248:249], v[248:249], v[82:83]
	v_exp_f32_e32 v98, v98
	v_cvt_pk_fp8_f32 v86, v92, v93
	v_exp_f32_e32 v99, v99
	v_cvt_pk_fp8_f32 v86, v94, v95 op_sel:[0,0,1]
	v_pk_add_f32 v[202:203], v[96:97], v[98:99]
	v_cvt_pk_fp8_f32 v87, v96, v97
	v_pk_add_f32 v[172:173], v[172:173], v[202:203]
	v_cvt_pk_fp8_f32 v87, v98, v99 op_sel:[0,0,1]
	v_pk_add_f32 v[248:249], v[248:249], v[172:173]
	s_nop 0
	v_add_f32_e32 v248, v248, v249
	v_cmp_lt_f32_e32 vcc, 0x43800000, v248
	s_cbranch_vccnz .Lbm2_Bg3_redo
	s_lshl_b32 s83, s32, 12
	s_add_u32 s30, s46, s83
	s_addc_u32 s31, s47, 0
	global_load_dwordx4 v[20:23], v79, s[30:31]
	global_load_dwordx4 v[24:27], v79, s[30:31] offset:1024
	global_load_dwordx4 v[28:31], v79, s[30:31] offset:2048
	global_load_dwordx4 v[32:35], v79, s[30:31] offset:3072
	v_add_f32_e32 v197, v197, v248
	s_waitcnt vmcnt(8)
	v_mfma_f32_16x16x32_fp8_fp8 v[148:151], v[52:53], v[84:85], v[148:151]
	v_mfma_f32_16x16x32_fp8_fp8 v[152:155], v[54:55], v[84:85], v[152:155]
	v_mfma_f32_16x16x32_fp8_fp8 v[156:159], v[56:57], v[84:85], v[156:159]
	v_mfma_f32_16x16x32_fp8_fp8 v[160:163], v[58:59], v[84:85], v[160:163]
	v_mfma_f32_16x16x32_fp8_fp8 v[148:151], v[60:61], v[86:87], v[148:151]
	v_mfma_f32_16x16x32_fp8_fp8 v[152:155], v[62:63], v[86:87], v[152:155]
	v_mfma_f32_16x16x32_fp8_fp8 v[156:159], v[64:65], v[86:87], v[156:159]
	v_mfma_f32_16x16x32_fp8_fp8 v[160:163], v[66:67], v[86:87], v[160:163]
	s_branch .Lbm2_Bg3_skip

.Lbm3_nostag:
.Lbm3_blkA:
	s_lshl_b32 s29, s27, 12
	s_add_u32 s30, s62, s29
	s_addc_u32 s31, s63, 0
	global_load_dwordx4 v[52:55], v79, s[30:31]
	global_load_dwordx4 v[56:59], v79, s[30:31] offset:1024
	global_load_dwordx4 v[60:63], v79, s[30:31] offset:2048
	global_load_dwordx4 v[64:67], v79, s[30:31] offset:3072
	s_add_i32 s50, s35, 3
	s_add_i32 s9, s25, -1
	s_min_i32 s50, s50, s9
	s_lshl_b32 s9, s50, 2
	s_add_i32 s9, s9, s46
	v_mov_b32_e32 v76, s9
	ds_read_b32 v76, v76 offset:16384
	s_cmp_ge_i32 s38, s21
	s_cselect_b32 s50, 1, 0
	s_bfe_u32 s29, s48, 0x40000
	s_cmp_eq_u32 s29, 0
	s_cbranch_scc1 .Lbm3_Ag0_skip
	s_waitcnt vmcnt(12)
	v_mfma_f32_16x16x32_fp8_fp8 v[84:87], v[2:3], v[164:165], 0
	v_mfma_f32_16x16x32_fp8_fp8 v[84:87], v[4:5], v[166:167], v[84:87]
	v_mfma_f32_16x16x32_fp8_fp8 v[88:91], v[6:7], v[164:165], 0
	v_mfma_f32_16x16x32_fp8_fp8 v[88:91], v[8:9], v[166:167], v[88:91]
	v_and_b32_e32 v199, s29, v244
	s_cmp_eq_u32 s50, 1
	v_cmp_ne_u32_e32 vcc, 0, v199
	s_cbranch_scc1 .Lbm3_Ag0_near0
	v_add_f32_e32 v200, v81, v190
	v_cndmask_b32_e32 v200, v77, v200, vcc
	s_cmp_eq_u32 s35, 0
	s_cbranch_scc1 .Lbm3_Ag0_first0
	v_mfma_f32_16x16x32_fp8_fp8 v[92:95], v[12:13], v[164:165], 0
	v_mfma_f32_16x16x32_fp8_fp8 v[92:95], v[14:15], v[166:167], v[92:95]
	v_pk_fma_f32 v[84:85], v[84:85], s[10:11], v[200:201] op_sel_hi:[1,1,0]
	v_pk_fma_f32 v[86:87], v[86:87], s[10:11], v[200:201] op_sel_hi:[1,1,0]
	v_mfma_f32_16x16x32_fp8_fp8 v[96:99], v[16:17], v[164:165], 0
	v_mfma_f32_16x16x32_fp8_fp8 v[96:99], v[18:19], v[166:167], v[96:99]
	v_exp_f32_e32 v84, v84
	v_pk_fma_f32 v[88:89], v[88:89], s[10:11], v[200:201] op_sel_hi:[1,1,0]
	v_exp_f32_e32 v85, v85
	v_pk_fma_f32 v[90:91], v[90:91], s[10:11], v[200:201] op_sel_hi:[1,1,0]
	v_exp_f32_e32 v86, v86
	v_pk_fma_f32 v[92:93], v[92:93], s[10:11], v[200:201] op_sel_hi:[1,1,0]
	v_exp_f32_e32 v87, v87
	v_pk_fma_f32 v[94:95], v[94:95], s[10:11], v[200:201] op_sel_hi:[1,1,0]
	v_exp_f32_e32 v88, v88
	v_pk_fma_f32 v[96:97], v[96:97], s[10:11], v[200:201] op_sel_hi:[1,1,0]
	v_exp_f32_e32 v89, v89
	v_pk_fma_f32 v[98:99], v[98:99], s[10:11], v[200:201] op_sel_hi:[1,1,0]
	v_exp_f32_e32 v90, v90
	v_pk_add_f32 v[248:249], v[84:85], v[86:87]
	v_exp_f32_e32 v91, v91
	v_cvt_pk_fp8_f32 v84, v84, v85
	v_exp_f32_e32 v92, v92
	v_pk_add_f32 v[82:83], v[88:89], v[90:91]
	v_exp_f32_e32 v93, v93
	v_cvt_pk_fp8_f32 v84, v86, v87 op_sel:[0,0,1]
	v_exp_f32_e32 v94, v94
	v_cvt_pk_fp8_f32 v85, v88, v89
	v_exp_f32_e32 v95, v95
	v_cvt_pk_fp8_f32 v85, v90, v91 op_sel:[0,0,1]
	v_exp_f32_e32 v96, v96
	v_pk_add_f32 v[172:173], v[92:93], v[94:95]
	v_exp_f32_e32 v97, v97
	v_pk_add_f32 v[248:249], v[248:249], v[82:83]
	v_exp_f32_e32 v98, v98
	v_cvt_pk_fp8_f32 v86, v92, v93
	v_exp_f32_e32 v99, v99
	v_cvt_pk_fp8_f32 v86, v94, v95 op_sel:[0,0,1]
	v_pk_add_f32 v[202:203], v[96:97], v[98:99]
	v_cvt_pk_fp8_f32 v87, v96, v97
	v_pk_add_f32 v[172:173], v[172:173], v[202:203]
	v_cvt_pk_fp8_f32 v87, v98, v99 op_sel:[0,0,1]
	v_pk_add_f32 v[248:249], v[248:249], v[172:173]
	s_nop 0
	v_add_f32_e32 v248, v248, v249
	v_cmp_lt_f32_e32 vcc, 0x43800000, v248
	s_cbranch_vccnz .Lbm3_Ag0_redo
	s_lshr_b32 s83, s48, 4
	s_cmp_lg_u32 s83, 0
	s_cbranch_scc1 .Lbm3_Ag0_ks0
	s_lshl_b32 s83, s32, 12
	s_add_u32 s30, s40, s83
	s_addc_u32 s31, s41, 0
	global_load_dwordx4 v[2:5], v79, s[30:31]
	global_load_dwordx4 v[6:9], v79, s[30:31] offset:1024
	global_load_dwordx4 v[12:15], v79, s[30:31] offset:2048
	global_load_dwordx4 v[16:19], v79, s[30:31] offset:3072

.Lbm3_Ag0_skip:
	s_bfe_u32 s29, s48, 0x40004
	s_cmp_eq_u32 s29, 0
	s_cbranch_scc1 .Lbm3_Ag1_skip
	s_waitcnt vmcnt(12)
	v_mfma_f32_16x16x32_fp8_fp8 v[84:87], v[2:3], v[168:169], 0
	v_mfma_f32_16x16x32_fp8_fp8 v[84:87], v[4:5], v[170:171], v[84:87]
	v_mfma_f32_16x16x32_fp8_fp8 v[88:91], v[6:7], v[168:169], 0
	v_mfma_f32_16x16x32_fp8_fp8 v[88:91], v[8:9], v[170:171], v[88:91]
	v_and_b32_e32 v199, s29, v244
	s_cmp_eq_u32 s50, 1
	v_cmp_ne_u32_e32 vcc, 0, v199
	s_cbranch_scc1 .Lbm3_Ag1_near0
	v_add_f32_e32 v200, v81, v191
	v_cndmask_b32_e32 v200, v77, v200, vcc
	s_cmp_eq_u32 s35, 0
	s_cbranch_scc1 .Lbm3_Ag1_first0
	v_mfma_f32_16x16x32_fp8_fp8 v[92:95], v[12:13], v[168:169], 0
	v_mfma_f32_16x16x32_fp8_fp8 v[92:95], v[14:15], v[170:171], v[92:95]
	v_pk_fma_f32 v[84:85], v[84:85], s[10:11], v[200:201] op_sel_hi:[1,1,0]
	v_pk_fma_f32 v[86:87], v[86:87], s[10:11], v[200:201] op_sel_hi:[1,1,0]
	v_mfma_f32_16x16x32_fp8_fp8 v[96:99], v[16:17], v[168:169], 0
	v_mfma_f32_16x16x32_fp8_fp8 v[96:99], v[18:19], v[170:171], v[96:99]
	v_exp_f32_e32 v84, v84
	v_pk_fma_f32 v[88:89], v[88:89], s[10:11], v[200:201] op_sel_hi:[1,1,0]
	v_exp_f32_e32 v85, v85
	v_pk_fma_f32 v[90:91], v[90:91], s[10:11], v[200:201] op_sel_hi:[1,1,0]
	v_exp_f32_e32 v86, v86
	v_pk_fma_f32 v[92:93], v[92:93], s[10:11], v[200:201] op_sel_hi:[1,1,0]
	v_exp_f32_e32 v87, v87
	v_pk_fma_f32 v[94:95], v[94:95], s[10:11], v[200:201] op_sel_hi:[1,1,0]
	v_exp_f32_e32 v88, v88
	v_pk_fma_f32 v[96:97], v[96:97], s[10:11], v[200:201] op_sel_hi:[1,1,0]
	v_exp_f32_e32 v89, v89
	v_pk_fma_f32 v[98:99], v[98:99], s[10:11], v[200:201] op_sel_hi:[1,1,0]
	v_exp_f32_e32 v90, v90
	v_pk_add_f32 v[248:249], v[84:85], v[86:87]
	v_exp_f32_e32 v91, v91
	v_cvt_pk_fp8_f32 v84, v84, v85
	v_exp_f32_e32 v92, v92
	v_pk_add_f32 v[82:83], v[88:89], v[90:91]
	v_exp_f32_e32 v93, v93
	v_cvt_pk_fp8_f32 v84, v86, v87 op_sel:[0,0,1]
	v_exp_f32_e32 v94, v94
	v_cvt_pk_fp8_f32 v85, v88, v89
	v_exp_f32_e32 v95, v95
	v_cvt_pk_fp8_f32 v85, v90, v91 op_sel:[0,0,1]
	v_exp_f32_e32 v96, v96
	v_pk_add_f32 v[172:173], v[92:93], v[94:95]
	v_exp_f32_e32 v97, v97
	v_pk_add_f32 v[248:249], v[248:249], v[82:83]
	v_exp_f32_e32 v98, v98
	v_cvt_pk_fp8_f32 v86, v92, v93
	v_exp_f32_e32 v99, v99
	v_cvt_pk_fp8_f32 v86, v94, v95 op_sel:[0,0,1]
	v_pk_add_f32 v[202:203], v[96:97], v[98:99]
	v_cvt_pk_fp8_f32 v87, v96, v97
	v_pk_add_f32 v[172:173], v[172:173], v[202:203]
	v_cvt_pk_fp8_f32 v87, v98, v99 op_sel:[0,0,1]
	v_pk_add_f32 v[248:249], v[248:249], v[172:173]
	s_nop 0
	v_add_f32_e32 v248, v248, v249
	v_cmp_lt_f32_e32 vcc, 0x43800000, v248
	s_cbranch_vccnz .Lbm3_Ag1_redo
	s_lshr_b32 s83, s48, 8
	s_cmp_lg_u32 s83, 0
	s_cbranch_scc1 .Lbm3_Ag1_ks0
	s_lshl_b32 s83, s32, 12
	s_add_u32 s30, s40, s83
	s_addc_u32 s31, s41, 0
	global_load_dwordx4 v[2:5], v79, s[30:31]
	global_load_dwordx4 v[6:9], v79, s[30:31] offset:1024
	global_load_dwordx4 v[12:15], v79, s[30:31] offset:2048
	global_load_dwordx4 v[16:19], v79, s[30:31] offset:3072

.Lbm3_Ag1_skip:
	s_bfe_u32 s29, s48, 0x40008
	s_cmp_eq_u32 s29, 0
	s_cbranch_scc1 .Lbm3_Ag2_skip
	s_waitcnt vmcnt(12)
	v_mfma_f32_16x16x32_fp8_fp8 v[84:87], v[2:3], v[182:183], 0
	v_mfma_f32_16x16x32_fp8_fp8 v[84:87], v[4:5], v[184:185], v[84:87]
	v_mfma_f32_16x16x32_fp8_fp8 v[88:91], v[6:7], v[182:183], 0
	v_mfma_f32_16x16x32_fp8_fp8 v[88:91], v[8:9], v[184:185], v[88:91]
	v_and_b32_e32 v199, s29, v244
	s_cmp_eq_u32 s50, 1
	v_cmp_ne_u32_e32 vcc, 0, v199
	s_cbranch_scc1 .Lbm3_Ag2_near0
	v_add_f32_e32 v200, v81, v192
	v_cndmask_b32_e32 v200, v77, v200, vcc
	s_cmp_eq_u32 s35, 0
	s_cbranch_scc1 .Lbm3_Ag2_first0
	v_mfma_f32_16x16x32_fp8_fp8 v[92:95], v[12:13], v[182:183], 0
	v_mfma_f32_16x16x32_fp8_fp8 v[92:95], v[14:15], v[184:185], v[92:95]
	v_pk_fma_f32 v[84:85], v[84:85], s[10:11], v[200:201] op_sel_hi:[1,1,0]
	v_pk_fma_f32 v[86:87], v[86:87], s[10:11], v[200:201] op_sel_hi:[1,1,0]
	v_mfma_f32_16x16x32_fp8_fp8 v[96:99], v[16:17], v[182:183], 0
	v_mfma_f32_16x16x32_fp8_fp8 v[96:99], v[18:19], v[184:185], v[96:99]
	v_exp_f32_e32 v84, v84
	v_pk_fma_f32 v[88:89], v[88:89], s[10:11], v[200:201] op_sel_hi:[1,1,0]
	v_exp_f32_e32 v85, v85
	v_pk_fma_f32 v[90:91], v[90:91], s[10:11], v[200:201] op_sel_hi:[1,1,0]
	v_exp_f32_e32 v86, v86
	v_pk_fma_f32 v[92:93], v[92:93], s[10:11], v[200:201] op_sel_hi:[1,1,0]
	v_exp_f32_e32 v87, v87
	v_pk_fma_f32 v[94:95], v[94:95], s[10:11], v[200:201] op_sel_hi:[1,1,0]
	v_exp_f32_e32 v88, v88
	v_pk_fma_f32 v[96:97], v[96:97], s[10:11], v[200:201] op_sel_hi:[1,1,0]
	v_exp_f32_e32 v89, v89
	v_pk_fma_f32 v[98:99], v[98:99], s[10:11], v[200:201] op_sel_hi:[1,1,0]
	v_exp_f32_e32 v90, v90
	v_pk_add_f32 v[248:249], v[84:85], v[86:87]
	v_exp_f32_e32 v91, v91
	v_cvt_pk_fp8_f32 v84, v84, v85
	v_exp_f32_e32 v92, v92
	v_pk_add_f32 v[82:83], v[88:89], v[90:91]
	v_exp_f32_e32 v93, v93
	v_cvt_pk_fp8_f32 v84, v86, v87 op_sel:[0,0,1]
	v_exp_f32_e32 v94, v94
	v_cvt_pk_fp8_f32 v85, v88, v89
	v_exp_f32_e32 v95, v95
	v_cvt_pk_fp8_f32 v85, v90, v91 op_sel:[0,0,1]
	v_exp_f32_e32 v96, v96
	v_pk_add_f32 v[172:173], v[92:93], v[94:95]
	v_exp_f32_e32 v97, v97
	v_pk_add_f32 v[248:249], v[248:249], v[82:83]
	v_exp_f32_e32 v98, v98
	v_cvt_pk_fp8_f32 v86, v92, v93
	v_exp_f32_e32 v99, v99
	v_cvt_pk_fp8_f32 v86, v94, v95 op_sel:[0,0,1]
	v_pk_add_f32 v[202:203], v[96:97], v[98:99]
	v_cvt_pk_fp8_f32 v87, v96, v97
	v_pk_add_f32 v[172:173], v[172:173], v[202:203]
	v_cvt_pk_fp8_f32 v87, v98, v99 op_sel:[0,0,1]
	v_pk_add_f32 v[248:249], v[248:249], v[172:173]
	s_nop 0
	v_add_f32_e32 v248, v248, v249
	v_cmp_lt_f32_e32 vcc, 0x43800000, v248
	s_cbranch_vccnz .Lbm3_Ag2_redo
	s_lshr_b32 s83, s48, 12
	s_cmp_lg_u32 s83, 0
	s_cbranch_scc1 .Lbm3_Ag2_ks0
	s_lshl_b32 s83, s32, 12
	s_add_u32 s30, s40, s83
	s_addc_u32 s31, s41, 0
	global_load_dwordx4 v[2:5], v79, s[30:31]
	global_load_dwordx4 v[6:9], v79, s[30:31] offset:1024
	global_load_dwordx4 v[12:15], v79, s[30:31] offset:2048
	global_load_dwordx4 v[16:19], v79, s[30:31] offset:3072

.Lbm3_Ag2_skip:
	s_bfe_u32 s29, s48, 0x4000c
	s_cmp_eq_u32 s29, 0
	s_cbranch_scc1 .Lbm3_Ag3_skip
	s_waitcnt vmcnt(12)
	v_mfma_f32_16x16x32_fp8_fp8 v[84:87], v[2:3], v[186:187], 0
	v_mfma_f32_16x16x32_fp8_fp8 v[84:87], v[4:5], v[188:189], v[84:87]
	v_mfma_f32_16x16x32_fp8_fp8 v[88:91], v[6:7], v[186:187], 0
	v_mfma_f32_16x16x32_fp8_fp8 v[88:91], v[8:9], v[188:189], v[88:91]
	v_and_b32_e32 v199, s29, v244
	s_cmp_eq_u32 s50, 1
	v_cmp_ne_u32_e32 vcc, 0, v199
	s_cbranch_scc1 .Lbm3_Ag3_near0
	v_add_f32_e32 v200, v81, v193
	v_cndmask_b32_e32 v200, v77, v200, vcc
	s_cmp_eq_u32 s35, 0
	s_cbranch_scc1 .Lbm3_Ag3_first0
	v_mfma_f32_16x16x32_fp8_fp8 v[92:95], v[12:13], v[186:187], 0
	v_mfma_f32_16x16x32_fp8_fp8 v[92:95], v[14:15], v[188:189], v[92:95]
	v_pk_fma_f32 v[84:85], v[84:85], s[10:11], v[200:201] op_sel_hi:[1,1,0]
	v_pk_fma_f32 v[86:87], v[86:87], s[10:11], v[200:201] op_sel_hi:[1,1,0]
	v_mfma_f32_16x16x32_fp8_fp8 v[96:99], v[16:17], v[186:187], 0
	v_mfma_f32_16x16x32_fp8_fp8 v[96:99], v[18:19], v[188:189], v[96:99]
	v_exp_f32_e32 v84, v84
	v_pk_fma_f32 v[88:89], v[88:89], s[10:11], v[200:201] op_sel_hi:[1,1,0]
	v_exp_f32_e32 v85, v85
	v_pk_fma_f32 v[90:91], v[90:91], s[10:11], v[200:201] op_sel_hi:[1,1,0]
	v_exp_f32_e32 v86, v86
	v_pk_fma_f32 v[92:93], v[92:93], s[10:11], v[200:201] op_sel_hi:[1,1,0]
	v_exp_f32_e32 v87, v87
	v_pk_fma_f32 v[94:95], v[94:95], s[10:11], v[200:201] op_sel_hi:[1,1,0]
	v_exp_f32_e32 v88, v88
	v_pk_fma_f32 v[96:97], v[96:97], s[10:11], v[200:201] op_sel_hi:[1,1,0]
	v_exp_f32_e32 v89, v89
	v_pk_fma_f32 v[98:99], v[98:99], s[10:11], v[200:201] op_sel_hi:[1,1,0]
	v_exp_f32_e32 v90, v90
	v_pk_add_f32 v[248:249], v[84:85], v[86:87]
	v_exp_f32_e32 v91, v91
	v_cvt_pk_fp8_f32 v84, v84, v85
	v_exp_f32_e32 v92, v92
	v_pk_add_f32 v[82:83], v[88:89], v[90:91]
	v_exp_f32_e32 v93, v93
	v_cvt_pk_fp8_f32 v84, v86, v87 op_sel:[0,0,1]
	v_exp_f32_e32 v94, v94
	v_cvt_pk_fp8_f32 v85, v88, v89
	v_exp_f32_e32 v95, v95
	v_cvt_pk_fp8_f32 v85, v90, v91 op_sel:[0,0,1]
	v_exp_f32_e32 v96, v96
	v_pk_add_f32 v[172:173], v[92:93], v[94:95]
	v_exp_f32_e32 v97, v97
	v_pk_add_f32 v[248:249], v[248:249], v[82:83]
	v_exp_f32_e32 v98, v98
	v_cvt_pk_fp8_f32 v86, v92, v93
	v_exp_f32_e32 v99, v99
	v_cvt_pk_fp8_f32 v86, v94, v95 op_sel:[0,0,1]
	v_pk_add_f32 v[202:203], v[96:97], v[98:99]
	v_cvt_pk_fp8_f32 v87, v96, v97
	v_pk_add_f32 v[172:173], v[172:173], v[202:203]
	v_cvt_pk_fp8_f32 v87, v98, v99 op_sel:[0,0,1]
	v_pk_add_f32 v[248:249], v[248:249], v[172:173]
	s_nop 0
	v_add_f32_e32 v248, v248, v249
	v_cmp_lt_f32_e32 vcc, 0x43800000, v248
	s_cbranch_vccnz .Lbm3_Ag3_redo
	s_lshl_b32 s83, s32, 12
	s_add_u32 s30, s40, s83
	s_addc_u32 s31, s41, 0
	global_load_dwordx4 v[2:5], v79, s[30:31]
	global_load_dwordx4 v[6:9], v79, s[30:31] offset:1024
	global_load_dwordx4 v[12:15], v79, s[30:31] offset:2048
	global_load_dwordx4 v[16:19], v79, s[30:31] offset:3072
	v_add_f32_e32 v197, v197, v248
	s_waitcnt vmcnt(8)
	v_mfma_f32_16x16x32_fp8_fp8 v[148:151], v[36:37], v[84:85], v[148:151]
	v_mfma_f32_16x16x32_fp8_fp8 v[152:155], v[38:39], v[84:85], v[152:155]
	v_mfma_f32_16x16x32_fp8_fp8 v[156:159], v[40:41], v[84:85], v[156:159]
	v_mfma_f32_16x16x32_fp8_fp8 v[160:163], v[42:43], v[84:85], v[160:163]
	v_mfma_f32_16x16x32_fp8_fp8 v[148:151], v[44:45], v[86:87], v[148:151]
	v_mfma_f32_16x16x32_fp8_fp8 v[152:155], v[46:47], v[86:87], v[152:155]
	v_mfma_f32_16x16x32_fp8_fp8 v[156:159], v[48:49], v[86:87], v[156:159]
	v_mfma_f32_16x16x32_fp8_fp8 v[160:163], v[50:51], v[86:87], v[160:163]
	s_branch .Lbm3_Ag3_skip

.Lbm3_blkB:
	s_lshl_b32 s29, s27, 12
	s_add_u32 s30, s62, s29
	s_addc_u32 s31, s63, 0
	global_load_dwordx4 v[36:39], v79, s[30:31]
	global_load_dwordx4 v[40:43], v79, s[30:31] offset:1024
	global_load_dwordx4 v[44:47], v79, s[30:31] offset:2048
	global_load_dwordx4 v[48:51], v79, s[30:31] offset:3072
	s_add_i32 s50, s35, 3
	s_add_i32 s9, s25, -1
	s_min_i32 s50, s50, s9
	s_lshl_b32 s9, s50, 2
	s_add_i32 s9, s9, s46
	v_mov_b32_e32 v76, s9
	ds_read_b32 v76, v76 offset:16384
	s_cmp_ge_i32 s38, s21
	s_cselect_b32 s50, 1, 0
	s_bfe_u32 s29, s48, 0x40000
	s_cmp_eq_u32 s29, 0
	s_cbranch_scc1 .Lbm3_Bg0_skip
	s_waitcnt vmcnt(12)
	v_mfma_f32_16x16x32_fp8_fp8 v[84:87], v[20:21], v[164:165], 0
	v_mfma_f32_16x16x32_fp8_fp8 v[84:87], v[22:23], v[166:167], v[84:87]
	v_mfma_f32_16x16x32_fp8_fp8 v[88:91], v[24:25], v[164:165], 0
	v_mfma_f32_16x16x32_fp8_fp8 v[88:91], v[26:27], v[166:167], v[88:91]
	v_and_b32_e32 v199, s29, v244
	s_cmp_eq_u32 s50, 1
	v_cmp_ne_u32_e32 vcc, 0, v199
	s_cbranch_scc1 .Lbm3_Bg0_near0
	v_add_f32_e32 v200, v81, v190
	v_cndmask_b32_e32 v200, v77, v200, vcc
	s_cmp_eq_u32 s35, 0
	s_cbranch_scc1 .Lbm3_Bg0_first0
	v_mfma_f32_16x16x32_fp8_fp8 v[92:95], v[28:29], v[164:165], 0
	v_mfma_f32_16x16x32_fp8_fp8 v[92:95], v[30:31], v[166:167], v[92:95]
	v_pk_fma_f32 v[84:85], v[84:85], s[10:11], v[200:201] op_sel_hi:[1,1,0]
	v_pk_fma_f32 v[86:87], v[86:87], s[10:11], v[200:201] op_sel_hi:[1,1,0]
	v_mfma_f32_16x16x32_fp8_fp8 v[96:99], v[32:33], v[164:165], 0
	v_mfma_f32_16x16x32_fp8_fp8 v[96:99], v[34:35], v[166:167], v[96:99]
	v_exp_f32_e32 v84, v84
	v_pk_fma_f32 v[88:89], v[88:89], s[10:11], v[200:201] op_sel_hi:[1,1,0]
	v_exp_f32_e32 v85, v85
	v_pk_fma_f32 v[90:91], v[90:91], s[10:11], v[200:201] op_sel_hi:[1,1,0]
	v_exp_f32_e32 v86, v86
	v_pk_fma_f32 v[92:93], v[92:93], s[10:11], v[200:201] op_sel_hi:[1,1,0]
	v_exp_f32_e32 v87, v87
	v_pk_fma_f32 v[94:95], v[94:95], s[10:11], v[200:201] op_sel_hi:[1,1,0]
	v_exp_f32_e32 v88, v88
	v_pk_fma_f32 v[96:97], v[96:97], s[10:11], v[200:201] op_sel_hi:[1,1,0]
	v_exp_f32_e32 v89, v89
	v_pk_fma_f32 v[98:99], v[98:99], s[10:11], v[200:201] op_sel_hi:[1,1,0]
	v_exp_f32_e32 v90, v90
	v_pk_add_f32 v[248:249], v[84:85], v[86:87]
	v_exp_f32_e32 v91, v91
	v_cvt_pk_fp8_f32 v84, v84, v85
	v_exp_f32_e32 v92, v92
	v_pk_add_f32 v[82:83], v[88:89], v[90:91]
	v_exp_f32_e32 v93, v93
	v_cvt_pk_fp8_f32 v84, v86, v87 op_sel:[0,0,1]
	v_exp_f32_e32 v94, v94
	v_cvt_pk_fp8_f32 v85, v88, v89
	v_exp_f32_e32 v95, v95
	v_cvt_pk_fp8_f32 v85, v90, v91 op_sel:[0,0,1]
	v_exp_f32_e32 v96, v96
	v_pk_add_f32 v[172:173], v[92:93], v[94:95]
	v_exp_f32_e32 v97, v97
	v_pk_add_f32 v[248:249], v[248:249], v[82:83]
	v_exp_f32_e32 v98, v98
	v_cvt_pk_fp8_f32 v86, v92, v93
	v_exp_f32_e32 v99, v99
	v_cvt_pk_fp8_f32 v86, v94, v95 op_sel:[0,0,1]
	v_pk_add_f32 v[202:203], v[96:97], v[98:99]
	v_cvt_pk_fp8_f32 v87, v96, v97
	v_pk_add_f32 v[172:173], v[172:173], v[202:203]
	v_cvt_pk_fp8_f32 v87, v98, v99 op_sel:[0,0,1]
	v_pk_add_f32 v[248:249], v[248:249], v[172:173]
	s_nop 0
	v_add_f32_e32 v248, v248, v249
	v_cmp_lt_f32_e32 vcc, 0x43800000, v248
	s_cbranch_vccnz .Lbm3_Bg0_redo
	s_lshr_b32 s83, s48, 4
	s_cmp_lg_u32 s83, 0
	s_cbranch_scc1 .Lbm3_Bg0_ks0
	s_lshl_b32 s83, s32, 12
	s_add_u32 s30, s40, s83
	s_addc_u32 s31, s41, 0
	global_load_dwordx4 v[20:23], v79, s[30:31]
	global_load_dwordx4 v[24:27], v79, s[30:31] offset:1024
	global_load_dwordx4 v[28:31], v79, s[30:31] offset:2048
	global_load_dwordx4 v[32:35], v79, s[30:31] offset:3072

.Lbm3_Bg0_skip:
	s_bfe_u32 s29, s48, 0x40004
	s_cmp_eq_u32 s29, 0
	s_cbranch_scc1 .Lbm3_Bg1_skip
	s_waitcnt vmcnt(12)
	v_mfma_f32_16x16x32_fp8_fp8 v[84:87], v[20:21], v[168:169], 0
	v_mfma_f32_16x16x32_fp8_fp8 v[84:87], v[22:23], v[170:171], v[84:87]
	v_mfma_f32_16x16x32_fp8_fp8 v[88:91], v[24:25], v[168:169], 0
	v_mfma_f32_16x16x32_fp8_fp8 v[88:91], v[26:27], v[170:171], v[88:91]
	v_and_b32_e32 v199, s29, v244
	s_cmp_eq_u32 s50, 1
	v_cmp_ne_u32_e32 vcc, 0, v199
	s_cbranch_scc1 .Lbm3_Bg1_near0
	v_add_f32_e32 v200, v81, v191
	v_cndmask_b32_e32 v200, v77, v200, vcc
	s_cmp_eq_u32 s35, 0
	s_cbranch_scc1 .Lbm3_Bg1_first0
	v_mfma_f32_16x16x32_fp8_fp8 v[92:95], v[28:29], v[168:169], 0
	v_mfma_f32_16x16x32_fp8_fp8 v[92:95], v[30:31], v[170:171], v[92:95]
	v_pk_fma_f32 v[84:85], v[84:85], s[10:11], v[200:201] op_sel_hi:[1,1,0]
	v_pk_fma_f32 v[86:87], v[86:87], s[10:11], v[200:201] op_sel_hi:[1,1,0]
	v_mfma_f32_16x16x32_fp8_fp8 v[96:99], v[32:33], v[168:169], 0
	v_mfma_f32_16x16x32_fp8_fp8 v[96:99], v[34:35], v[170:171], v[96:99]
	v_exp_f32_e32 v84, v84
	v_pk_fma_f32 v[88:89], v[88:89], s[10:11], v[200:201] op_sel_hi:[1,1,0]
	v_exp_f32_e32 v85, v85
	v_pk_fma_f32 v[90:91], v[90:91], s[10:11], v[200:201] op_sel_hi:[1,1,0]
	v_exp_f32_e32 v86, v86
	v_pk_fma_f32 v[92:93], v[92:93], s[10:11], v[200:201] op_sel_hi:[1,1,0]
	v_exp_f32_e32 v87, v87
	v_pk_fma_f32 v[94:95], v[94:95], s[10:11], v[200:201] op_sel_hi:[1,1,0]
	v_exp_f32_e32 v88, v88
	v_pk_fma_f32 v[96:97], v[96:97], s[10:11], v[200:201] op_sel_hi:[1,1,0]
	v_exp_f32_e32 v89, v89
	v_pk_fma_f32 v[98:99], v[98:99], s[10:11], v[200:201] op_sel_hi:[1,1,0]
	v_exp_f32_e32 v90, v90
	v_pk_add_f32 v[248:249], v[84:85], v[86:87]
	v_exp_f32_e32 v91, v91
	v_cvt_pk_fp8_f32 v84, v84, v85
	v_exp_f32_e32 v92, v92
	v_pk_add_f32 v[82:83], v[88:89], v[90:91]
	v_exp_f32_e32 v93, v93
	v_cvt_pk_fp8_f32 v84, v86, v87 op_sel:[0,0,1]
	v_exp_f32_e32 v94, v94
	v_cvt_pk_fp8_f32 v85, v88, v89
	v_exp_f32_e32 v95, v95
	v_cvt_pk_fp8_f32 v85, v90, v91 op_sel:[0,0,1]
	v_exp_f32_e32 v96, v96
	v_pk_add_f32 v[172:173], v[92:93], v[94:95]
	v_exp_f32_e32 v97, v97
	v_pk_add_f32 v[248:249], v[248:249], v[82:83]
	v_exp_f32_e32 v98, v98
	v_cvt_pk_fp8_f32 v86, v92, v93
	v_exp_f32_e32 v99, v99
	v_cvt_pk_fp8_f32 v86, v94, v95 op_sel:[0,0,1]
	v_pk_add_f32 v[202:203], v[96:97], v[98:99]
	v_cvt_pk_fp8_f32 v87, v96, v97
	v_pk_add_f32 v[172:173], v[172:173], v[202:203]
	v_cvt_pk_fp8_f32 v87, v98, v99 op_sel:[0,0,1]
	v_pk_add_f32 v[248:249], v[248:249], v[172:173]
	s_nop 0
	v_add_f32_e32 v248, v248, v249
	v_cmp_lt_f32_e32 vcc, 0x43800000, v248
	s_cbranch_vccnz .Lbm3_Bg1_redo
	s_lshr_b32 s83, s48, 8
	s_cmp_lg_u32 s83, 0
	s_cbranch_scc1 .Lbm3_Bg1_ks0
	s_lshl_b32 s83, s32, 12
	s_add_u32 s30, s40, s83
	s_addc_u32 s31, s41, 0
	global_load_dwordx4 v[20:23], v79, s[30:31]
	global_load_dwordx4 v[24:27], v79, s[30:31] offset:1024
	global_load_dwordx4 v[28:31], v79, s[30:31] offset:2048
	global_load_dwordx4 v[32:35], v79, s[30:31] offset:3072

.Lbm3_Bg1_skip:
	s_bfe_u32 s29, s48, 0x40008
	s_cmp_eq_u32 s29, 0
	s_cbranch_scc1 .Lbm3_Bg2_skip
	s_waitcnt vmcnt(12)
	v_mfma_f32_16x16x32_fp8_fp8 v[84:87], v[20:21], v[182:183], 0
	v_mfma_f32_16x16x32_fp8_fp8 v[84:87], v[22:23], v[184:185], v[84:87]
	v_mfma_f32_16x16x32_fp8_fp8 v[88:91], v[24:25], v[182:183], 0
	v_mfma_f32_16x16x32_fp8_fp8 v[88:91], v[26:27], v[184:185], v[88:91]
	v_and_b32_e32 v199, s29, v244
	s_cmp_eq_u32 s50, 1
	v_cmp_ne_u32_e32 vcc, 0, v199
	s_cbranch_scc1 .Lbm3_Bg2_near0
	v_add_f32_e32 v200, v81, v192
	v_cndmask_b32_e32 v200, v77, v200, vcc
	s_cmp_eq_u32 s35, 0
	s_cbranch_scc1 .Lbm3_Bg2_first0
	v_mfma_f32_16x16x32_fp8_fp8 v[92:95], v[28:29], v[182:183], 0
	v_mfma_f32_16x16x32_fp8_fp8 v[92:95], v[30:31], v[184:185], v[92:95]
	v_pk_fma_f32 v[84:85], v[84:85], s[10:11], v[200:201] op_sel_hi:[1,1,0]
	v_pk_fma_f32 v[86:87], v[86:87], s[10:11], v[200:201] op_sel_hi:[1,1,0]
	v_mfma_f32_16x16x32_fp8_fp8 v[96:99], v[32:33], v[182:183], 0
	v_mfma_f32_16x16x32_fp8_fp8 v[96:99], v[34:35], v[184:185], v[96:99]
	v_exp_f32_e32 v84, v84
	v_pk_fma_f32 v[88:89], v[88:89], s[10:11], v[200:201] op_sel_hi:[1,1,0]
	v_exp_f32_e32 v85, v85
	v_pk_fma_f32 v[90:91], v[90:91], s[10:11], v[200:201] op_sel_hi:[1,1,0]
	v_exp_f32_e32 v86, v86
	v_pk_fma_f32 v[92:93], v[92:93], s[10:11], v[200:201] op_sel_hi:[1,1,0]
	v_exp_f32_e32 v87, v87
	v_pk_fma_f32 v[94:95], v[94:95], s[10:11], v[200:201] op_sel_hi:[1,1,0]
	v_exp_f32_e32 v88, v88
	v_pk_fma_f32 v[96:97], v[96:97], s[10:11], v[200:201] op_sel_hi:[1,1,0]
	v_exp_f32_e32 v89, v89
	v_pk_fma_f32 v[98:99], v[98:99], s[10:11], v[200:201] op_sel_hi:[1,1,0]
	v_exp_f32_e32 v90, v90
	v_pk_add_f32 v[248:249], v[84:85], v[86:87]
	v_exp_f32_e32 v91, v91
	v_cvt_pk_fp8_f32 v84, v84, v85
	v_exp_f32_e32 v92, v92
	v_pk_add_f32 v[82:83], v[88:89], v[90:91]
	v_exp_f32_e32 v93, v93
	v_cvt_pk_fp8_f32 v84, v86, v87 op_sel:[0,0,1]
	v_exp_f32_e32 v94, v94
	v_cvt_pk_fp8_f32 v85, v88, v89
	v_exp_f32_e32 v95, v95
	v_cvt_pk_fp8_f32 v85, v90, v91 op_sel:[0,0,1]
	v_exp_f32_e32 v96, v96
	v_pk_add_f32 v[172:173], v[92:93], v[94:95]
	v_exp_f32_e32 v97, v97
	v_pk_add_f32 v[248:249], v[248:249], v[82:83]
	v_exp_f32_e32 v98, v98
	v_cvt_pk_fp8_f32 v86, v92, v93
	v_exp_f32_e32 v99, v99
	v_cvt_pk_fp8_f32 v86, v94, v95 op_sel:[0,0,1]
	v_pk_add_f32 v[202:203], v[96:97], v[98:99]
	v_cvt_pk_fp8_f32 v87, v96, v97
	v_pk_add_f32 v[172:173], v[172:173], v[202:203]
	v_cvt_pk_fp8_f32 v87, v98, v99 op_sel:[0,0,1]
	v_pk_add_f32 v[248:249], v[248:249], v[172:173]
	s_nop 0
	v_add_f32_e32 v248, v248, v249
	v_cmp_lt_f32_e32 vcc, 0x43800000, v248
	s_cbranch_vccnz .Lbm3_Bg2_redo
	s_lshr_b32 s83, s48, 12
	s_cmp_lg_u32 s83, 0
	s_cbranch_scc1 .Lbm3_Bg2_ks0
	s_lshl_b32 s83, s32, 12
	s_add_u32 s30, s40, s83
	s_addc_u32 s31, s41, 0
	global_load_dwordx4 v[20:23], v79, s[30:31]
	global_load_dwordx4 v[24:27], v79, s[30:31] offset:1024
	global_load_dwordx4 v[28:31], v79, s[30:31] offset:2048
	global_load_dwordx4 v[32:35], v79, s[30:31] offset:3072

.Lbm3_Bg2_skip:
	s_bfe_u32 s29, s48, 0x4000c
	s_cmp_eq_u32 s29, 0
	s_cbranch_scc1 .Lbm3_Bg3_skip
	s_waitcnt vmcnt(12)
	v_mfma_f32_16x16x32_fp8_fp8 v[84:87], v[20:21], v[186:187], 0
	v_mfma_f32_16x16x32_fp8_fp8 v[84:87], v[22:23], v[188:189], v[84:87]
	v_mfma_f32_16x16x32_fp8_fp8 v[88:91], v[24:25], v[186:187], 0
	v_mfma_f32_16x16x32_fp8_fp8 v[88:91], v[26:27], v[188:189], v[88:91]
	v_and_b32_e32 v199, s29, v244
	s_cmp_eq_u32 s50, 1
	v_cmp_ne_u32_e32 vcc, 0, v199
	s_cbranch_scc1 .Lbm3_Bg3_near0
	v_add_f32_e32 v200, v81, v193
	v_cndmask_b32_e32 v200, v77, v200, vcc
	s_cmp_eq_u32 s35, 0
	s_cbranch_scc1 .Lbm3_Bg3_first0
	v_mfma_f32_16x16x32_fp8_fp8 v[92:95], v[28:29], v[186:187], 0
	v_mfma_f32_16x16x32_fp8_fp8 v[92:95], v[30:31], v[188:189], v[92:95]
	v_pk_fma_f32 v[84:85], v[84:85], s[10:11], v[200:201] op_sel_hi:[1,1,0]
	v_pk_fma_f32 v[86:87], v[86:87], s[10:11], v[200:201] op_sel_hi:[1,1,0]
	v_mfma_f32_16x16x32_fp8_fp8 v[96:99], v[32:33], v[186:187], 0
	v_mfma_f32_16x16x32_fp8_fp8 v[96:99], v[34:35], v[188:189], v[96:99]
	v_exp_f32_e32 v84, v84
	v_pk_fma_f32 v[88:89], v[88:89], s[10:11], v[200:201] op_sel_hi:[1,1,0]
	v_exp_f32_e32 v85, v85
	v_pk_fma_f32 v[90:91], v[90:91], s[10:11], v[200:201] op_sel_hi:[1,1,0]
	v_exp_f32_e32 v86, v86
	v_pk_fma_f32 v[92:93], v[92:93], s[10:11], v[200:201] op_sel_hi:[1,1,0]
	v_exp_f32_e32 v87, v87
	v_pk_fma_f32 v[94:95], v[94:95], s[10:11], v[200:201] op_sel_hi:[1,1,0]
	v_exp_f32_e32 v88, v88
	v_pk_fma_f32 v[96:97], v[96:97], s[10:11], v[200:201] op_sel_hi:[1,1,0]
	v_exp_f32_e32 v89, v89
	v_pk_fma_f32 v[98:99], v[98:99], s[10:11], v[200:201] op_sel_hi:[1,1,0]
	v_exp_f32_e32 v90, v90
	v_pk_add_f32 v[248:249], v[84:85], v[86:87]
	v_exp_f32_e32 v91, v91
	v_cvt_pk_fp8_f32 v84, v84, v85
	v_exp_f32_e32 v92, v92
	v_pk_add_f32 v[82:83], v[88:89], v[90:91]
	v_exp_f32_e32 v93, v93
	v_cvt_pk_fp8_f32 v84, v86, v87 op_sel:[0,0,1]
	v_exp_f32_e32 v94, v94
	v_cvt_pk_fp8_f32 v85, v88, v89
	v_exp_f32_e32 v95, v95
	v_cvt_pk_fp8_f32 v85, v90, v91 op_sel:[0,0,1]
	v_exp_f32_e32 v96, v96
	v_pk_add_f32 v[172:173], v[92:93], v[94:95]
	v_exp_f32_e32 v97, v97
	v_pk_add_f32 v[248:249], v[248:249], v[82:83]
	v_exp_f32_e32 v98, v98
	v_cvt_pk_fp8_f32 v86, v92, v93
	v_exp_f32_e32 v99, v99
	v_cvt_pk_fp8_f32 v86, v94, v95 op_sel:[0,0,1]
	v_pk_add_f32 v[202:203], v[96:97], v[98:99]
	v_cvt_pk_fp8_f32 v87, v96, v97
	v_pk_add_f32 v[172:173], v[172:173], v[202:203]
	v_cvt_pk_fp8_f32 v87, v98, v99 op_sel:[0,0,1]
	v_pk_add_f32 v[248:249], v[248:249], v[172:173]
	s_nop 0
	v_add_f32_e32 v248, v248, v249
	v_cmp_lt_f32_e32 vcc, 0x43800000, v248
	s_cbranch_vccnz .Lbm3_Bg3_redo
	s_lshl_b32 s83, s32, 12
	s_add_u32 s30, s40, s83
	s_addc_u32 s31, s41, 0
	global_load_dwordx4 v[20:23], v79, s[30:31]
	global_load_dwordx4 v[24:27], v79, s[30:31] offset:1024
	global_load_dwordx4 v[28:31], v79, s[30:31] offset:2048
	global_load_dwordx4 v[32:35], v79, s[30:31] offset:3072
	v_add_f32_e32 v197, v197, v248
	s_waitcnt vmcnt(8)
	v_mfma_f32_16x16x32_fp8_fp8 v[148:151], v[52:53], v[84:85], v[148:151]
	v_mfma_f32_16x16x32_fp8_fp8 v[152:155], v[54:55], v[84:85], v[152:155]
	v_mfma_f32_16x16x32_fp8_fp8 v[156:159], v[56:57], v[84:85], v[156:159]
	v_mfma_f32_16x16x32_fp8_fp8 v[160:163], v[58:59], v[84:85], v[160:163]
	v_mfma_f32_16x16x32_fp8_fp8 v[148:151], v[60:61], v[86:87], v[148:151]
	v_mfma_f32_16x16x32_fp8_fp8 v[152:155], v[62:63], v[86:87], v[152:155]
	v_mfma_f32_16x16x32_fp8_fp8 v[156:159], v[64:65], v[86:87], v[156:159]
	v_mfma_f32_16x16x32_fp8_fp8 v[160:163], v[66:67], v[86:87], v[160:163]
	s_branch .Lbm3_Bg3_skip
